# selected loop: not-selected mask folded into the QK product as one extra K-step (bf16 -1e30 x 1.0), 16 per-tile v_cndmask on the probabilities removed
# baseline (speedup 1.0000x reference)
.Lsel_pre:
	s_mov_b32 s76, 0
	v_mad_i64_i32 v[30:31], vcc, v100, s90, v[30:31]
	v_mad_i64_i32 v[104:105], vcc, v100, s90, v[104:105]
	s_mov_b32 s81, 0
	s_movk_i32 s82, 0x4900
	s_mov_b32 s83, 0x9200
	v_mov_b32_e32 v0, s77
	ds_read_b32 v107, v0
	ds_read_b32 v160, v0 offset:4
	ds_read_b32 v184, v0 offset:8
	ds_read_b32 v182, v0 offset:12
	s_waitcnt lgkmcnt(0)
	v_readfirstlane_b32 s1, v107
	v_readfirstlane_b32 s0, v160
	v_readfirstlane_b32 s86, v184
	s_nop 1
	s_lshr_b32 s98, s1, 5
	s_and_b32 s98, s98, 3
	s_lshl_b32 s98, s98, 2
	v_add_u32_e32 v107, s98, v103
	ds_read_b32 v107, v107
	s_lshr_b32 s98, s0, 5
	s_and_b32 s98, s98, 3
	s_lshl_b32 s98, s98, 2
	v_add_u32_e32 v160, s98, v103
	ds_read_b32 v160, v160
	s_waitcnt lgkmcnt(0)
	s_and_b32 s98, s1, 31
	v_bfe_u32 v107, v107, s98, 1
	v_cmp_eq_u32_e64 s[72:73], 0, v107
	s_and_b32 s98, s0, 31
	v_bfe_u32 v160, v160, s98, 1
	v_cmp_eq_u32_e64 s[100:101], 0, v160
	v_mov_b32_e32 v152, 0x3f80
	v_cmp_gt_u32_e32 vcc, 32, v186
	v_mov_b32_e32 v153, 0
	v_mov_b32_e32 v154, 0
	v_cndmask_b32_e32 v152, 0, v152, vcc
	v_mov_b32_e32 v155, 0
	v_mov_b32_e32 v157, 0
	v_mov_b32_e32 v158, 0
	v_mov_b32_e32 v159, 0
	v_cndmask_b32_e64 v156, 0, -1, s[72:73]
	v_and_b32_e32 v156, 0xf149, v156
	s_cmp_ge_u32 s79, 2
	s_cbranch_scc1 .Lsel_pre_n1
	s_mov_b64 s[100:101], -1
.Lsel_pre_n1:
	s_nop 1
	s_cmp_lg_u64 s[72:73], -1
	s_cbranch_scc0 .Lsel_step_0
	v_add_u32_e32 v0, s81, v208
	ds_read_b128 v[108:111], v0
	ds_read_b128 v[112:115], v0 offset:4608
	ds_read_b128 v[116:119], v0 offset:32
	ds_read_b128 v[120:123], v0 offset:4640
	s_waitcnt lgkmcnt(3)
	v_mfma_f32_32x32x16_bf16 v[80:95], v[108:111], v[128:131], v[2:17]
	ds_read_b128 v[108:111], v0 offset:64
	s_waitcnt lgkmcnt(3)
	v_mfma_f32_32x32x16_bf16 v[64:79], v[112:115], v[128:131], v[2:17]
	ds_read_b128 v[112:115], v0 offset:4672
	s_waitcnt lgkmcnt(3)
	v_mfma_f32_32x32x16_bf16 v[80:95], v[116:119], v[132:135], v[80:95]
	ds_read_b128 v[116:119], v0 offset:96
	s_waitcnt lgkmcnt(3)
	v_mfma_f32_32x32x16_bf16 v[64:79], v[120:123], v[132:135], v[64:79]
	ds_read_b128 v[120:123], v0 offset:4704
	s_waitcnt lgkmcnt(3)
	v_mfma_f32_32x32x16_bf16 v[80:95], v[108:111], v[136:139], v[80:95]
	s_waitcnt lgkmcnt(2)
	v_mfma_f32_32x32x16_bf16 v[64:79], v[112:115], v[136:139], v[64:79]
	s_waitcnt lgkmcnt(1)
	v_mfma_f32_32x32x16_bf16 v[80:95], v[116:119], v[140:143], v[80:95]
	v_mfma_f32_32x32x16_bf16 v[80:95], v[152:155], v[156:159], v[80:95]
	s_waitcnt lgkmcnt(0)
	v_mfma_f32_32x32x16_bf16 v[64:79], v[120:123], v[140:143], v[64:79]
	v_mfma_f32_32x32x16_bf16 v[64:79], v[152:155], v[156:159], v[64:79]

.Lsel_nogl_0:
	v_cndmask_b32_e64 v156, 0, -1, s[100:101]
	v_and_b32_e32 v156, 0xf149, v156
	s_lshr_b32 s98, s86, 5
	s_and_b32 s98, s98, 3
	s_lshl_b32 s98, s98, 2
	v_add_u32_e32 v184, s98, v103
	ds_read_b32 v184, v184
	s_cmp_lg_u64 s[100:101], -1
	s_cbranch_scc0 .Lsel_noN_0
	s_cmp_lg_u64 s[72:73], -1
	s_cbranch_scc0 .Lsel_Nonly_0
	v_add_u32_e32 v0, s82, v208
	ds_read_b128 v[108:111], v0
	ds_read_b128 v[112:115], v0 offset:4608
	ds_read_b128 v[116:119], v0 offset:32
	ds_read_b128 v[120:123], v0 offset:4640
	s_add_u32 s1, s76, 1
	s_cmp_lg_u32 s1, s79
	s_cbranch_scc1 .Lsel_nodiag_0b
	v_cndmask_b32_e64 v80, v80, v185, s[6:7]
	v_cndmask_b32_e64 v64, v64, v185, s[8:9]
	v_cndmask_b32_e64 v81, v185, v81, s[10:11]
	v_cndmask_b32_e64 v65, v65, v185, s[12:13]
	v_cndmask_b32_e64 v82, v82, v185, s[14:15]
	v_cndmask_b32_e64 v66, v66, v185, s[16:17]
	v_cndmask_b32_e64 v83, v83, v185, s[18:19]
	v_cndmask_b32_e64 v67, v67, v185, s[20:21]
	v_cndmask_b32_e64 v84, v84, v185, s[22:23]
	v_cndmask_b32_e64 v68, v68, v185, s[24:25]
	v_cndmask_b32_e64 v85, v85, v185, s[26:27]
	v_cndmask_b32_e64 v69, v69, v185, s[28:29]
	v_cndmask_b32_e64 v86, v86, v185, s[30:31]
	v_cndmask_b32_e64 v70, v70, v185, s[34:35]
	v_cndmask_b32_e64 v87, v87, v185, s[36:37]
	v_cndmask_b32_e64 v71, v71, v185, s[38:39]
	v_cndmask_b32_e64 v88, v88, v185, s[40:41]
	v_cndmask_b32_e64 v72, v72, v185, s[42:43]
	v_cndmask_b32_e64 v89, v89, v185, s[44:45]
	v_cndmask_b32_e64 v73, v73, v185, s[46:47]
	v_cndmask_b32_e64 v90, v90, v185, s[48:49]
	v_cndmask_b32_e64 v74, v74, v185, s[50:51]
	v_cndmask_b32_e64 v91, v91, v185, s[52:53]
	v_cndmask_b32_e64 v75, v75, v185, s[54:55]
	v_cndmask_b32_e64 v92, v92, v185, s[56:57]
	v_cndmask_b32_e64 v76, v76, v185, s[58:59]
	v_cndmask_b32_e64 v93, v93, v185, s[60:61]
	v_cndmask_b32_e64 v77, v77, v185, s[62:63]
	v_cndmask_b32_e64 v94, v94, v185, s[64:65]
	v_cndmask_b32_e64 v78, v78, v185, s[66:67]
	v_cndmask_b32_e64 v95, v95, v185, s[68:69]
	v_cndmask_b32_e64 v79, v79, v185, s[70:71]
.Lsel_nodiag_0b:
	v_add_u32_e32 v187, s81, v208
	ds_read_b128 v[124:127], v187 offset:9216
	ds_read_b128 v[144:147], v187 offset:13824
	ds_read_b128 v[148:151], v187 offset:9248
	v_exp_f32_e32 v80, v80
	v_exp_f32_e32 v81, v81
	v_exp_f32_e32 v82, v82
	v_exp_f32_e32 v83, v83
	s_waitcnt lgkmcnt(6)
	v_mfma_f32_32x32x16_bf16 v[238:253], v[108:111], v[128:131], v[2:17]
	ds_read_b128 v[108:111], v0 offset:64
	v_exp_f32_e32 v84, v84
	v_exp_f32_e32 v85, v85
	v_exp_f32_e32 v86, v86
	v_exp_f32_e32 v87, v87
	s_waitcnt lgkmcnt(6)
	v_mfma_f32_32x32x16_bf16 v[222:237], v[112:115], v[128:131], v[2:17]
	ds_read_b128 v[112:115], v0 offset:4672
	v_add_f32_e32 v164, 0, v80
	v_add_f32_e32 v165, 0, v81
	v_add_f32_e32 v164, v82, v164
	v_add_f32_e32 v165, v83, v165
	v_cvt_pk_bf16_f32 v80, v80, v81
	v_cvt_pk_bf16_f32 v81, v82, v83
	v_add_f32_e32 v164, v84, v164
	v_add_f32_e32 v165, v85, v165
	v_add_f32_e32 v164, v86, v164
	v_add_f32_e32 v165, v87, v165
	v_cvt_pk_bf16_f32 v82, v84, v85
	v_cvt_pk_bf16_f32 v83, v86, v87
	v_exp_f32_e32 v88, v88
	v_exp_f32_e32 v89, v89
	s_waitcnt lgkmcnt(4)
	v_mfma_f32_32x32x16_bf16 v[48:63], v[124:127], v[80:83], v[48:63]
	ds_read_b128 v[124:127], v187 offset:13856
	v_exp_f32_e32 v90, v90
	v_exp_f32_e32 v91, v91
	s_waitcnt lgkmcnt(4)
	v_mfma_f32_32x32x16_bf16 v[32:47], v[144:147], v[80:83], v[32:47]
	ds_read_b128 v[144:147], v187 offset:9280
	v_exp_f32_e32 v92, v92
	v_exp_f32_e32 v93, v93
	v_mfma_f32_32x32x16_bf16 v[238:253], v[116:119], v[132:135], v[238:253]
	ds_read_b128 v[116:119], v0 offset:96
	v_exp_f32_e32 v94, v94
	v_exp_f32_e32 v95, v95
	v_mfma_f32_32x32x16_bf16 v[222:237], v[120:123], v[132:135], v[222:237]
	ds_read_b128 v[120:123], v0 offset:4704
	v_add_f32_e32 v164, v88, v164
	v_add_f32_e32 v165, v89, v165
	v_add_f32_e32 v164, v90, v164
	v_add_f32_e32 v165, v91, v165
	v_cvt_pk_bf16_f32 v88, v88, v89
	v_cvt_pk_bf16_f32 v89, v90, v91
	v_add_f32_e32 v164, v92, v164
	v_add_f32_e32 v165, v93, v165
	v_add_f32_e32 v164, v94, v164
	v_add_f32_e32 v165, v95, v165
	v_cvt_pk_bf16_f32 v90, v92, v93
	v_cvt_pk_bf16_f32 v91, v94, v95
	v_exp_f32_e32 v64, v64
	v_exp_f32_e32 v65, v65
	s_waitcnt lgkmcnt(6)
	v_mfma_f32_32x32x16_bf16 v[48:63], v[148:151], v[88:91], v[48:63]
	ds_read_b128 v[148:151], v187 offset:13888
	v_exp_f32_e32 v66, v66
	v_exp_f32_e32 v67, v67
	s_waitcnt lgkmcnt(4)
	v_mfma_f32_32x32x16_bf16 v[32:47], v[124:127], v[88:91], v[32:47]
	ds_read_b128 v[124:127], v187 offset:9312
	v_exp_f32_e32 v68, v68
	v_exp_f32_e32 v69, v69
	v_mfma_f32_32x32x16_bf16 v[238:253], v[108:111], v[136:139], v[238:253]
	v_exp_f32_e32 v70, v70
	v_exp_f32_e32 v71, v71
	v_mfma_f32_32x32x16_bf16 v[222:237], v[112:115], v[136:139], v[222:237]
	v_add_f32_e32 v164, v64, v164
	v_add_f32_e32 v165, v65, v165
	v_add_f32_e32 v164, v66, v164
	v_add_f32_e32 v165, v67, v165
	v_cvt_pk_bf16_f32 v64, v64, v65
	v_cvt_pk_bf16_f32 v65, v66, v67
	v_add_f32_e32 v164, v68, v164
	v_add_f32_e32 v165, v69, v165
	v_add_f32_e32 v164, v70, v164
	v_add_f32_e32 v165, v71, v165
	v_cvt_pk_bf16_f32 v66, v68, v69
	v_cvt_pk_bf16_f32 v67, v70, v71
	v_exp_f32_e32 v72, v72
	v_exp_f32_e32 v73, v73
	s_waitcnt lgkmcnt(4)
	v_mfma_f32_32x32x16_bf16 v[48:63], v[144:147], v[64:67], v[48:63]
	ds_read_b128 v[144:147], v187 offset:13920
	v_exp_f32_e32 v74, v74
	v_exp_f32_e32 v75, v75
	s_waitcnt lgkmcnt(2)
	v_mfma_f32_32x32x16_bf16 v[32:47], v[148:151], v[64:67], v[32:47]
	v_exp_f32_e32 v76, v76
	v_exp_f32_e32 v77, v77
	v_mfma_f32_32x32x16_bf16 v[238:253], v[116:119], v[140:143], v[238:253]
	v_mfma_f32_32x32x16_bf16 v[238:253], v[152:155], v[156:159], v[238:253]
	v_exp_f32_e32 v78, v78
	v_exp_f32_e32 v79, v79
	v_mfma_f32_32x32x16_bf16 v[222:237], v[120:123], v[140:143], v[222:237]
	v_mfma_f32_32x32x16_bf16 v[222:237], v[152:155], v[156:159], v[222:237]
	v_add_f32_e32 v164, v72, v164
	v_add_f32_e32 v165, v73, v165
	v_add_f32_e32 v164, v74, v164
	v_add_f32_e32 v165, v75, v165
	v_cvt_pk_bf16_f32 v72, v72, v73
	v_cvt_pk_bf16_f32 v73, v74, v75
	v_add_f32_e32 v164, v76, v164
	v_add_f32_e32 v165, v77, v165
	v_add_f32_e32 v164, v78, v164
	v_add_f32_e32 v165, v79, v165
	v_cvt_pk_bf16_f32 v74, v76, v77
	v_cvt_pk_bf16_f32 v75, v78, v79
	s_nop 1
	s_waitcnt lgkmcnt(1)
	v_mfma_f32_32x32x16_bf16 v[48:63], v[124:127], v[72:75], v[48:63]
	s_waitcnt lgkmcnt(0)
	v_mfma_f32_32x32x16_bf16 v[32:47], v[144:147], v[72:75], v[32:47]
	v_add_f32_e32 v164, v164, v165
	v_cndmask_b32_e64 v164, v164, 0, s[72:73]
	v_add_f32_e32 v106, v106, v164
	v_cmp_lt_f32_e32 vcc, 0x43800000, v164
	s_cbranch_vccz .Lsel_noresc_0b
	s_nop 15
	s_nop 15
	v_mov_b32_e32 v107, v164
	s_nop 1
	v_permlane32_swap_b32_e32 v164, v107
	v_add_f32_e32 v164, v164, v107
	v_log_f32_e32 v160, v164
	s_nop 0
	v_max_f32_e32 v160, 0, v160
	v_exp_f32_e64 v162, -v160
	v_sub_f32_e32 v2, v2, v160
	v_sub_f32_e32 v3, v3, v160
	v_sub_f32_e32 v4, v4, v160
	v_sub_f32_e32 v5, v5, v160
	v_sub_f32_e32 v6, v6, v160
	v_sub_f32_e32 v7, v7, v160
	v_sub_f32_e32 v8, v8, v160
	v_sub_f32_e32 v9, v9, v160
	v_sub_f32_e32 v10, v10, v160
	v_sub_f32_e32 v11, v11, v160
	v_sub_f32_e32 v12, v12, v160
	v_sub_f32_e32 v13, v13, v160
	v_sub_f32_e32 v14, v14, v160
	v_sub_f32_e32 v15, v15, v160
	v_sub_f32_e32 v16, v16, v160
	v_sub_f32_e32 v17, v17, v160
	v_mul_f32_e32 v106, v106, v162
	v_pk_mul_f32 v[48:49], v[48:49], v[162:163] op_sel_hi:[1,0]
	v_pk_mul_f32 v[32:33], v[32:33], v[162:163] op_sel_hi:[1,0]
	v_pk_mul_f32 v[50:51], v[50:51], v[162:163] op_sel_hi:[1,0]
	v_pk_mul_f32 v[34:35], v[34:35], v[162:163] op_sel_hi:[1,0]
	v_pk_mul_f32 v[52:53], v[52:53], v[162:163] op_sel_hi:[1,0]
	v_pk_mul_f32 v[36:37], v[36:37], v[162:163] op_sel_hi:[1,0]
	v_pk_mul_f32 v[54:55], v[54:55], v[162:163] op_sel_hi:[1,0]
	v_pk_mul_f32 v[38:39], v[38:39], v[162:163] op_sel_hi:[1,0]
	v_pk_mul_f32 v[56:57], v[56:57], v[162:163] op_sel_hi:[1,0]
	v_pk_mul_f32 v[40:41], v[40:41], v[162:163] op_sel_hi:[1,0]
	v_pk_mul_f32 v[58:59], v[58:59], v[162:163] op_sel_hi:[1,0]
	v_pk_mul_f32 v[42:43], v[42:43], v[162:163] op_sel_hi:[1,0]
	v_pk_mul_f32 v[60:61], v[60:61], v[162:163] op_sel_hi:[1,0]
	v_pk_mul_f32 v[44:45], v[44:45], v[162:163] op_sel_hi:[1,0]
	v_pk_mul_f32 v[62:63], v[62:63], v[162:163] op_sel_hi:[1,0]
	v_pk_mul_f32 v[46:47], v[46:47], v[162:163] op_sel_hi:[1,0]
	v_pk_add_f32 v[238:239], v[238:239], v[160:161] op_sel_hi:[1,0] neg_lo:[0,1] neg_hi:[0,1]
	v_pk_add_f32 v[222:223], v[222:223], v[160:161] op_sel_hi:[1,0] neg_lo:[0,1] neg_hi:[0,1]
	v_pk_add_f32 v[240:241], v[240:241], v[160:161] op_sel_hi:[1,0] neg_lo:[0,1] neg_hi:[0,1]
	v_pk_add_f32 v[224:225], v[224:225], v[160:161] op_sel_hi:[1,0] neg_lo:[0,1] neg_hi:[0,1]
	v_pk_add_f32 v[242:243], v[242:243], v[160:161] op_sel_hi:[1,0] neg_lo:[0,1] neg_hi:[0,1]
	v_pk_add_f32 v[226:227], v[226:227], v[160:161] op_sel_hi:[1,0] neg_lo:[0,1] neg_hi:[0,1]
	v_pk_add_f32 v[244:245], v[244:245], v[160:161] op_sel_hi:[1,0] neg_lo:[0,1] neg_hi:[0,1]
	v_pk_add_f32 v[228:229], v[228:229], v[160:161] op_sel_hi:[1,0] neg_lo:[0,1] neg_hi:[0,1]
	v_pk_add_f32 v[246:247], v[246:247], v[160:161] op_sel_hi:[1,0] neg_lo:[0,1] neg_hi:[0,1]
	v_pk_add_f32 v[230:231], v[230:231], v[160:161] op_sel_hi:[1,0] neg_lo:[0,1] neg_hi:[0,1]
	v_pk_add_f32 v[248:249], v[248:249], v[160:161] op_sel_hi:[1,0] neg_lo:[0,1] neg_hi:[0,1]
	v_pk_add_f32 v[232:233], v[232:233], v[160:161] op_sel_hi:[1,0] neg_lo:[0,1] neg_hi:[0,1]
	v_pk_add_f32 v[250:251], v[250:251], v[160:161] op_sel_hi:[1,0] neg_lo:[0,1] neg_hi:[0,1]
	v_pk_add_f32 v[234:235], v[234:235], v[160:161] op_sel_hi:[1,0] neg_lo:[0,1] neg_hi:[0,1]
	v_pk_add_f32 v[252:253], v[252:253], v[160:161] op_sel_hi:[1,0] neg_lo:[0,1] neg_hi:[0,1]
	v_pk_add_f32 v[236:237], v[236:237], v[160:161] op_sel_hi:[1,0] neg_lo:[0,1] neg_hi:[0,1]
	s_nop 1

.Lsel_Nonly_0:
	v_add_u32_e32 v0, s82, v208
	ds_read_b128 v[108:111], v0
	ds_read_b128 v[112:115], v0 offset:4608
	ds_read_b128 v[116:119], v0 offset:32
	ds_read_b128 v[120:123], v0 offset:4640
	s_waitcnt lgkmcnt(3)
	v_mfma_f32_32x32x16_bf16 v[238:253], v[108:111], v[128:131], v[2:17]
	ds_read_b128 v[108:111], v0 offset:64
	s_waitcnt lgkmcnt(3)
	v_mfma_f32_32x32x16_bf16 v[222:237], v[112:115], v[128:131], v[2:17]
	ds_read_b128 v[112:115], v0 offset:4672
	s_waitcnt lgkmcnt(3)
	v_mfma_f32_32x32x16_bf16 v[238:253], v[116:119], v[132:135], v[238:253]
	ds_read_b128 v[116:119], v0 offset:96
	s_waitcnt lgkmcnt(3)
	v_mfma_f32_32x32x16_bf16 v[222:237], v[120:123], v[132:135], v[222:237]
	ds_read_b128 v[120:123], v0 offset:4704
	s_waitcnt lgkmcnt(3)
	v_mfma_f32_32x32x16_bf16 v[238:253], v[108:111], v[136:139], v[238:253]
	s_waitcnt lgkmcnt(2)
	v_mfma_f32_32x32x16_bf16 v[222:237], v[112:115], v[136:139], v[222:237]
	s_waitcnt lgkmcnt(1)
	v_mfma_f32_32x32x16_bf16 v[238:253], v[116:119], v[140:143], v[238:253]
	v_mfma_f32_32x32x16_bf16 v[238:253], v[152:155], v[156:159], v[238:253]
	s_waitcnt lgkmcnt(0)
	v_mfma_f32_32x32x16_bf16 v[222:237], v[120:123], v[140:143], v[222:237]
	v_mfma_f32_32x32x16_bf16 v[222:237], v[152:155], v[156:159], v[222:237]
	s_branch .Lsel_tail_0

.Lsel_nodiag_0c:
	v_add_u32_e32 v187, s81, v208
	ds_read_b128 v[124:127], v187 offset:9216
	ds_read_b128 v[144:147], v187 offset:13824
	ds_read_b128 v[148:151], v187 offset:9248
	v_exp_f32_e32 v80, v80
	v_exp_f32_e32 v81, v81
	v_exp_f32_e32 v82, v82
	v_exp_f32_e32 v83, v83
	v_exp_f32_e32 v84, v84
	v_exp_f32_e32 v85, v85
	v_exp_f32_e32 v86, v86
	v_exp_f32_e32 v87, v87
	v_add_f32_e32 v164, 0, v80
	v_add_f32_e32 v165, 0, v81
	v_add_f32_e32 v164, v82, v164
	v_add_f32_e32 v165, v83, v165
	v_cvt_pk_bf16_f32 v80, v80, v81
	v_cvt_pk_bf16_f32 v81, v82, v83
	v_add_f32_e32 v164, v84, v164
	v_add_f32_e32 v165, v85, v165
	v_add_f32_e32 v164, v86, v164
	v_add_f32_e32 v165, v87, v165
	v_cvt_pk_bf16_f32 v82, v84, v85
	v_cvt_pk_bf16_f32 v83, v86, v87
	v_exp_f32_e32 v88, v88
	v_exp_f32_e32 v89, v89
	s_waitcnt lgkmcnt(2)
	v_mfma_f32_32x32x16_bf16 v[48:63], v[124:127], v[80:83], v[48:63]
	ds_read_b128 v[124:127], v187 offset:13856
	v_exp_f32_e32 v90, v90
	v_exp_f32_e32 v91, v91
	s_waitcnt lgkmcnt(2)
	v_mfma_f32_32x32x16_bf16 v[32:47], v[144:147], v[80:83], v[32:47]
	ds_read_b128 v[144:147], v187 offset:9280
	v_exp_f32_e32 v92, v92
	v_exp_f32_e32 v93, v93
	v_exp_f32_e32 v94, v94
	v_exp_f32_e32 v95, v95
	v_add_f32_e32 v164, v88, v164
	v_add_f32_e32 v165, v89, v165
	v_add_f32_e32 v164, v90, v164
	v_add_f32_e32 v165, v91, v165
	v_cvt_pk_bf16_f32 v88, v88, v89
	v_cvt_pk_bf16_f32 v89, v90, v91
	v_add_f32_e32 v164, v92, v164
	v_add_f32_e32 v165, v93, v165
	v_add_f32_e32 v164, v94, v164
	v_add_f32_e32 v165, v95, v165
	v_cvt_pk_bf16_f32 v90, v92, v93
	v_cvt_pk_bf16_f32 v91, v94, v95
	v_exp_f32_e32 v64, v64
	v_exp_f32_e32 v65, v65
	s_waitcnt lgkmcnt(2)
	v_mfma_f32_32x32x16_bf16 v[48:63], v[148:151], v[88:91], v[48:63]
	ds_read_b128 v[148:151], v187 offset:13888
	v_exp_f32_e32 v66, v66
	v_exp_f32_e32 v67, v67
	s_waitcnt lgkmcnt(2)
	v_mfma_f32_32x32x16_bf16 v[32:47], v[124:127], v[88:91], v[32:47]
	ds_read_b128 v[124:127], v187 offset:9312
	v_exp_f32_e32 v68, v68
	v_exp_f32_e32 v69, v69
	v_exp_f32_e32 v70, v70
	v_exp_f32_e32 v71, v71
	v_add_f32_e32 v164, v64, v164
	v_add_f32_e32 v165, v65, v165
	v_add_f32_e32 v164, v66, v164
	v_add_f32_e32 v165, v67, v165
	v_cvt_pk_bf16_f32 v64, v64, v65
	v_cvt_pk_bf16_f32 v65, v66, v67
	v_add_f32_e32 v164, v68, v164
	v_add_f32_e32 v165, v69, v165
	v_add_f32_e32 v164, v70, v164
	v_add_f32_e32 v165, v71, v165
	v_cvt_pk_bf16_f32 v66, v68, v69
	v_cvt_pk_bf16_f32 v67, v70, v71
	v_exp_f32_e32 v72, v72
	v_exp_f32_e32 v73, v73
	s_waitcnt lgkmcnt(2)
	v_mfma_f32_32x32x16_bf16 v[48:63], v[144:147], v[64:67], v[48:63]
	ds_read_b128 v[144:147], v187 offset:13920
	v_exp_f32_e32 v74, v74
	v_exp_f32_e32 v75, v75
	s_waitcnt lgkmcnt(2)
	v_mfma_f32_32x32x16_bf16 v[32:47], v[148:151], v[64:67], v[32:47]
	v_exp_f32_e32 v76, v76
	v_exp_f32_e32 v77, v77
	v_exp_f32_e32 v78, v78
	v_exp_f32_e32 v79, v79
	v_add_f32_e32 v164, v72, v164
	v_add_f32_e32 v165, v73, v165
	v_add_f32_e32 v164, v74, v164
	v_add_f32_e32 v165, v75, v165
	v_cvt_pk_bf16_f32 v72, v72, v73
	v_cvt_pk_bf16_f32 v73, v74, v75
	v_add_f32_e32 v164, v76, v164
	v_add_f32_e32 v165, v77, v165
	v_add_f32_e32 v164, v78, v164
	v_add_f32_e32 v165, v79, v165
	v_cvt_pk_bf16_f32 v74, v76, v77
	v_cvt_pk_bf16_f32 v75, v78, v79
	s_nop 1
	s_waitcnt lgkmcnt(1)
	v_mfma_f32_32x32x16_bf16 v[48:63], v[124:127], v[72:75], v[48:63]
	s_waitcnt lgkmcnt(0)
	v_mfma_f32_32x32x16_bf16 v[32:47], v[144:147], v[72:75], v[32:47]
	v_add_f32_e32 v164, v164, v165
	v_cndmask_b32_e64 v164, v164, 0, s[72:73]
	v_add_f32_e32 v106, v106, v164
	v_cmp_lt_f32_e32 vcc, 0x43800000, v164
	s_cbranch_vccz .Lsel_noresc_0c
	s_nop 15
	s_nop 15
	v_mov_b32_e32 v107, v164
	s_nop 1
	v_permlane32_swap_b32_e32 v164, v107
	v_add_f32_e32 v164, v164, v107
	v_log_f32_e32 v160, v164
	s_nop 0
	v_max_f32_e32 v160, 0, v160
	v_exp_f32_e64 v162, -v160
	v_sub_f32_e32 v2, v2, v160
	v_sub_f32_e32 v3, v3, v160
	v_sub_f32_e32 v4, v4, v160
	v_sub_f32_e32 v5, v5, v160
	v_sub_f32_e32 v6, v6, v160
	v_sub_f32_e32 v7, v7, v160
	v_sub_f32_e32 v8, v8, v160
	v_sub_f32_e32 v9, v9, v160
	v_sub_f32_e32 v10, v10, v160
	v_sub_f32_e32 v11, v11, v160
	v_sub_f32_e32 v12, v12, v160
	v_sub_f32_e32 v13, v13, v160
	v_sub_f32_e32 v14, v14, v160
	v_sub_f32_e32 v15, v15, v160
	v_sub_f32_e32 v16, v16, v160
	v_sub_f32_e32 v17, v17, v160
	v_mul_f32_e32 v106, v106, v162
	v_pk_mul_f32 v[48:49], v[48:49], v[162:163] op_sel_hi:[1,0]
	v_pk_mul_f32 v[32:33], v[32:33], v[162:163] op_sel_hi:[1,0]
	v_pk_mul_f32 v[50:51], v[50:51], v[162:163] op_sel_hi:[1,0]
	v_pk_mul_f32 v[34:35], v[34:35], v[162:163] op_sel_hi:[1,0]
	v_pk_mul_f32 v[52:53], v[52:53], v[162:163] op_sel_hi:[1,0]
	v_pk_mul_f32 v[36:37], v[36:37], v[162:163] op_sel_hi:[1,0]
	v_pk_mul_f32 v[54:55], v[54:55], v[162:163] op_sel_hi:[1,0]
	v_pk_mul_f32 v[38:39], v[38:39], v[162:163] op_sel_hi:[1,0]
	v_pk_mul_f32 v[56:57], v[56:57], v[162:163] op_sel_hi:[1,0]
	v_pk_mul_f32 v[40:41], v[40:41], v[162:163] op_sel_hi:[1,0]
	v_pk_mul_f32 v[58:59], v[58:59], v[162:163] op_sel_hi:[1,0]
	v_pk_mul_f32 v[42:43], v[42:43], v[162:163] op_sel_hi:[1,0]
	v_pk_mul_f32 v[60:61], v[60:61], v[162:163] op_sel_hi:[1,0]
	v_pk_mul_f32 v[44:45], v[44:45], v[162:163] op_sel_hi:[1,0]
	v_pk_mul_f32 v[62:63], v[62:63], v[162:163] op_sel_hi:[1,0]
	v_pk_mul_f32 v[46:47], v[46:47], v[162:163] op_sel_hi:[1,0]
	s_nop 1

.Lsel_nogl_1:
	v_cndmask_b32_e64 v156, 0, -1, s[100:101]
	v_and_b32_e32 v156, 0xf149, v156
	s_lshr_b32 s98, s86, 5
	s_and_b32 s98, s98, 3
	s_lshl_b32 s98, s98, 2
	v_add_u32_e32 v184, s98, v103
	ds_read_b32 v184, v184
	s_cmp_lg_u64 s[100:101], -1
	s_cbranch_scc0 .Lsel_noN_1
	s_cmp_lg_u64 s[72:73], -1
	s_cbranch_scc0 .Lsel_Nonly_1
	v_add_u32_e32 v0, s82, v208
	ds_read_b128 v[108:111], v0
	ds_read_b128 v[112:115], v0 offset:4608
	ds_read_b128 v[116:119], v0 offset:32
	ds_read_b128 v[120:123], v0 offset:4640
	s_add_u32 s1, s76, 1
	s_cmp_lg_u32 s1, s79
	s_cbranch_scc1 .Lsel_nodiag_1b
	v_cndmask_b32_e64 v238, v238, v185, s[6:7]
	v_cndmask_b32_e64 v222, v222, v185, s[8:9]
	v_cndmask_b32_e64 v239, v185, v239, s[10:11]
	v_cndmask_b32_e64 v223, v223, v185, s[12:13]
	v_cndmask_b32_e64 v240, v240, v185, s[14:15]
	v_cndmask_b32_e64 v224, v224, v185, s[16:17]
	v_cndmask_b32_e64 v241, v241, v185, s[18:19]
	v_cndmask_b32_e64 v225, v225, v185, s[20:21]
	v_cndmask_b32_e64 v242, v242, v185, s[22:23]
	v_cndmask_b32_e64 v226, v226, v185, s[24:25]
	v_cndmask_b32_e64 v243, v243, v185, s[26:27]
	v_cndmask_b32_e64 v227, v227, v185, s[28:29]
	v_cndmask_b32_e64 v244, v244, v185, s[30:31]
	v_cndmask_b32_e64 v228, v228, v185, s[34:35]
	v_cndmask_b32_e64 v245, v245, v185, s[36:37]
	v_cndmask_b32_e64 v229, v229, v185, s[38:39]
	v_cndmask_b32_e64 v246, v246, v185, s[40:41]
	v_cndmask_b32_e64 v230, v230, v185, s[42:43]
	v_cndmask_b32_e64 v247, v247, v185, s[44:45]
	v_cndmask_b32_e64 v231, v231, v185, s[46:47]
	v_cndmask_b32_e64 v248, v248, v185, s[48:49]
	v_cndmask_b32_e64 v232, v232, v185, s[50:51]
	v_cndmask_b32_e64 v249, v249, v185, s[52:53]
	v_cndmask_b32_e64 v233, v233, v185, s[54:55]
	v_cndmask_b32_e64 v250, v250, v185, s[56:57]
	v_cndmask_b32_e64 v234, v234, v185, s[58:59]
	v_cndmask_b32_e64 v251, v251, v185, s[60:61]
	v_cndmask_b32_e64 v235, v235, v185, s[62:63]
	v_cndmask_b32_e64 v252, v252, v185, s[64:65]
	v_cndmask_b32_e64 v236, v236, v185, s[66:67]
	v_cndmask_b32_e64 v253, v253, v185, s[68:69]
	v_cndmask_b32_e64 v237, v237, v185, s[70:71]
.Lsel_nodiag_1b:
	v_add_u32_e32 v187, s81, v208
	ds_read_b128 v[124:127], v187 offset:9216
	ds_read_b128 v[144:147], v187 offset:13824
	ds_read_b128 v[148:151], v187 offset:9248
	v_exp_f32_e32 v238, v238
	v_exp_f32_e32 v239, v239
	v_exp_f32_e32 v240, v240
	v_exp_f32_e32 v241, v241
	s_waitcnt lgkmcnt(6)
	v_mfma_f32_32x32x16_bf16 v[80:95], v[108:111], v[128:131], v[2:17]
	ds_read_b128 v[108:111], v0 offset:64
	v_exp_f32_e32 v242, v242
	v_exp_f32_e32 v243, v243
	v_exp_f32_e32 v244, v244
	v_exp_f32_e32 v245, v245
	s_waitcnt lgkmcnt(6)
	v_mfma_f32_32x32x16_bf16 v[64:79], v[112:115], v[128:131], v[2:17]
	ds_read_b128 v[112:115], v0 offset:4672
	v_add_f32_e32 v164, 0, v238
	v_add_f32_e32 v165, 0, v239
	v_add_f32_e32 v164, v240, v164
	v_add_f32_e32 v165, v241, v165
	v_cvt_pk_bf16_f32 v238, v238, v239
	v_cvt_pk_bf16_f32 v239, v240, v241
	v_add_f32_e32 v164, v242, v164
	v_add_f32_e32 v165, v243, v165
	v_add_f32_e32 v164, v244, v164
	v_add_f32_e32 v165, v245, v165
	v_cvt_pk_bf16_f32 v240, v242, v243
	v_cvt_pk_bf16_f32 v241, v244, v245
	v_exp_f32_e32 v246, v246
	v_exp_f32_e32 v247, v247
	s_waitcnt lgkmcnt(4)
	v_mfma_f32_32x32x16_bf16 v[48:63], v[124:127], v[238:241], v[48:63]
	ds_read_b128 v[124:127], v187 offset:13856
	v_exp_f32_e32 v248, v248
	v_exp_f32_e32 v249, v249
	s_waitcnt lgkmcnt(4)
	v_mfma_f32_32x32x16_bf16 v[32:47], v[144:147], v[238:241], v[32:47]
	ds_read_b128 v[144:147], v187 offset:9280
	v_exp_f32_e32 v250, v250
	v_exp_f32_e32 v251, v251
	v_mfma_f32_32x32x16_bf16 v[80:95], v[116:119], v[132:135], v[80:95]
	ds_read_b128 v[116:119], v0 offset:96
	v_exp_f32_e32 v252, v252
	v_exp_f32_e32 v253, v253
	v_mfma_f32_32x32x16_bf16 v[64:79], v[120:123], v[132:135], v[64:79]
	ds_read_b128 v[120:123], v0 offset:4704
	v_add_f32_e32 v164, v246, v164
	v_add_f32_e32 v165, v247, v165
	v_add_f32_e32 v164, v248, v164
	v_add_f32_e32 v165, v249, v165
	v_cvt_pk_bf16_f32 v246, v246, v247
	v_cvt_pk_bf16_f32 v247, v248, v249
	v_add_f32_e32 v164, v250, v164
	v_add_f32_e32 v165, v251, v165
	v_add_f32_e32 v164, v252, v164
	v_add_f32_e32 v165, v253, v165
	v_cvt_pk_bf16_f32 v248, v250, v251
	v_cvt_pk_bf16_f32 v249, v252, v253
	v_exp_f32_e32 v222, v222
	v_exp_f32_e32 v223, v223
	s_waitcnt lgkmcnt(6)
	v_mfma_f32_32x32x16_bf16 v[48:63], v[148:151], v[246:249], v[48:63]
	ds_read_b128 v[148:151], v187 offset:13888
	v_exp_f32_e32 v224, v224
	v_exp_f32_e32 v225, v225
	s_waitcnt lgkmcnt(4)
	v_mfma_f32_32x32x16_bf16 v[32:47], v[124:127], v[246:249], v[32:47]
	ds_read_b128 v[124:127], v187 offset:9312
	v_exp_f32_e32 v226, v226
	v_exp_f32_e32 v227, v227
	v_mfma_f32_32x32x16_bf16 v[80:95], v[108:111], v[136:139], v[80:95]
	v_exp_f32_e32 v228, v228
	v_exp_f32_e32 v229, v229
	v_mfma_f32_32x32x16_bf16 v[64:79], v[112:115], v[136:139], v[64:79]
	v_add_f32_e32 v164, v222, v164
	v_add_f32_e32 v165, v223, v165
	v_add_f32_e32 v164, v224, v164
	v_add_f32_e32 v165, v225, v165
	v_cvt_pk_bf16_f32 v222, v222, v223
	v_cvt_pk_bf16_f32 v223, v224, v225
	v_add_f32_e32 v164, v226, v164
	v_add_f32_e32 v165, v227, v165
	v_add_f32_e32 v164, v228, v164
	v_add_f32_e32 v165, v229, v165
	v_cvt_pk_bf16_f32 v224, v226, v227
	v_cvt_pk_bf16_f32 v225, v228, v229
	v_exp_f32_e32 v230, v230
	v_exp_f32_e32 v231, v231
	s_waitcnt lgkmcnt(4)
	v_mfma_f32_32x32x16_bf16 v[48:63], v[144:147], v[222:225], v[48:63]
	ds_read_b128 v[144:147], v187 offset:13920
	v_exp_f32_e32 v232, v232
	v_exp_f32_e32 v233, v233
	s_waitcnt lgkmcnt(2)
	v_mfma_f32_32x32x16_bf16 v[32:47], v[148:151], v[222:225], v[32:47]
	v_exp_f32_e32 v234, v234
	v_exp_f32_e32 v235, v235
	v_mfma_f32_32x32x16_bf16 v[80:95], v[116:119], v[140:143], v[80:95]
	v_mfma_f32_32x32x16_bf16 v[80:95], v[152:155], v[156:159], v[80:95]
	v_exp_f32_e32 v236, v236
	v_exp_f32_e32 v237, v237
	v_mfma_f32_32x32x16_bf16 v[64:79], v[120:123], v[140:143], v[64:79]
	v_mfma_f32_32x32x16_bf16 v[64:79], v[152:155], v[156:159], v[64:79]
	v_add_f32_e32 v164, v230, v164
	v_add_f32_e32 v165, v231, v165
	v_add_f32_e32 v164, v232, v164
	v_add_f32_e32 v165, v233, v165
	v_cvt_pk_bf16_f32 v230, v230, v231
	v_cvt_pk_bf16_f32 v231, v232, v233
	v_add_f32_e32 v164, v234, v164
	v_add_f32_e32 v165, v235, v165
	v_add_f32_e32 v164, v236, v164
	v_add_f32_e32 v165, v237, v165
	v_cvt_pk_bf16_f32 v232, v234, v235
	v_cvt_pk_bf16_f32 v233, v236, v237
	s_nop 1
	s_waitcnt lgkmcnt(1)
	v_mfma_f32_32x32x16_bf16 v[48:63], v[124:127], v[230:233], v[48:63]
	s_waitcnt lgkmcnt(0)
	v_mfma_f32_32x32x16_bf16 v[32:47], v[144:147], v[230:233], v[32:47]
	v_add_f32_e32 v164, v164, v165
	v_cndmask_b32_e64 v164, v164, 0, s[72:73]
	v_add_f32_e32 v106, v106, v164
	v_cmp_lt_f32_e32 vcc, 0x43800000, v164
	s_cbranch_vccz .Lsel_noresc_1b
	s_nop 15
	s_nop 15
	v_mov_b32_e32 v107, v164
	s_nop 1
	v_permlane32_swap_b32_e32 v164, v107
	v_add_f32_e32 v164, v164, v107
	v_log_f32_e32 v160, v164
	s_nop 0
	v_max_f32_e32 v160, 0, v160
	v_exp_f32_e64 v162, -v160
	v_sub_f32_e32 v2, v2, v160
	v_sub_f32_e32 v3, v3, v160
	v_sub_f32_e32 v4, v4, v160
	v_sub_f32_e32 v5, v5, v160
	v_sub_f32_e32 v6, v6, v160
	v_sub_f32_e32 v7, v7, v160
	v_sub_f32_e32 v8, v8, v160
	v_sub_f32_e32 v9, v9, v160
	v_sub_f32_e32 v10, v10, v160
	v_sub_f32_e32 v11, v11, v160
	v_sub_f32_e32 v12, v12, v160
	v_sub_f32_e32 v13, v13, v160
	v_sub_f32_e32 v14, v14, v160
	v_sub_f32_e32 v15, v15, v160
	v_sub_f32_e32 v16, v16, v160
	v_sub_f32_e32 v17, v17, v160
	v_mul_f32_e32 v106, v106, v162
	v_pk_mul_f32 v[48:49], v[48:49], v[162:163] op_sel_hi:[1,0]
	v_pk_mul_f32 v[32:33], v[32:33], v[162:163] op_sel_hi:[1,0]
	v_pk_mul_f32 v[50:51], v[50:51], v[162:163] op_sel_hi:[1,0]
	v_pk_mul_f32 v[34:35], v[34:35], v[162:163] op_sel_hi:[1,0]
	v_pk_mul_f32 v[52:53], v[52:53], v[162:163] op_sel_hi:[1,0]
	v_pk_mul_f32 v[36:37], v[36:37], v[162:163] op_sel_hi:[1,0]
	v_pk_mul_f32 v[54:55], v[54:55], v[162:163] op_sel_hi:[1,0]
	v_pk_mul_f32 v[38:39], v[38:39], v[162:163] op_sel_hi:[1,0]
	v_pk_mul_f32 v[56:57], v[56:57], v[162:163] op_sel_hi:[1,0]
	v_pk_mul_f32 v[40:41], v[40:41], v[162:163] op_sel_hi:[1,0]
	v_pk_mul_f32 v[58:59], v[58:59], v[162:163] op_sel_hi:[1,0]
	v_pk_mul_f32 v[42:43], v[42:43], v[162:163] op_sel_hi:[1,0]
	v_pk_mul_f32 v[60:61], v[60:61], v[162:163] op_sel_hi:[1,0]
	v_pk_mul_f32 v[44:45], v[44:45], v[162:163] op_sel_hi:[1,0]
	v_pk_mul_f32 v[62:63], v[62:63], v[162:163] op_sel_hi:[1,0]
	v_pk_mul_f32 v[46:47], v[46:47], v[162:163] op_sel_hi:[1,0]
	v_pk_add_f32 v[80:81], v[80:81], v[160:161] op_sel_hi:[1,0] neg_lo:[0,1] neg_hi:[0,1]
	v_pk_add_f32 v[64:65], v[64:65], v[160:161] op_sel_hi:[1,0] neg_lo:[0,1] neg_hi:[0,1]
	v_pk_add_f32 v[82:83], v[82:83], v[160:161] op_sel_hi:[1,0] neg_lo:[0,1] neg_hi:[0,1]
	v_pk_add_f32 v[66:67], v[66:67], v[160:161] op_sel_hi:[1,0] neg_lo:[0,1] neg_hi:[0,1]
	v_pk_add_f32 v[84:85], v[84:85], v[160:161] op_sel_hi:[1,0] neg_lo:[0,1] neg_hi:[0,1]
	v_pk_add_f32 v[68:69], v[68:69], v[160:161] op_sel_hi:[1,0] neg_lo:[0,1] neg_hi:[0,1]
	v_pk_add_f32 v[86:87], v[86:87], v[160:161] op_sel_hi:[1,0] neg_lo:[0,1] neg_hi:[0,1]
	v_pk_add_f32 v[70:71], v[70:71], v[160:161] op_sel_hi:[1,0] neg_lo:[0,1] neg_hi:[0,1]
	v_pk_add_f32 v[88:89], v[88:89], v[160:161] op_sel_hi:[1,0] neg_lo:[0,1] neg_hi:[0,1]
	v_pk_add_f32 v[72:73], v[72:73], v[160:161] op_sel_hi:[1,0] neg_lo:[0,1] neg_hi:[0,1]
	v_pk_add_f32 v[90:91], v[90:91], v[160:161] op_sel_hi:[1,0] neg_lo:[0,1] neg_hi:[0,1]
	v_pk_add_f32 v[74:75], v[74:75], v[160:161] op_sel_hi:[1,0] neg_lo:[0,1] neg_hi:[0,1]
	v_pk_add_f32 v[92:93], v[92:93], v[160:161] op_sel_hi:[1,0] neg_lo:[0,1] neg_hi:[0,1]
	v_pk_add_f32 v[76:77], v[76:77], v[160:161] op_sel_hi:[1,0] neg_lo:[0,1] neg_hi:[0,1]
	v_pk_add_f32 v[94:95], v[94:95], v[160:161] op_sel_hi:[1,0] neg_lo:[0,1] neg_hi:[0,1]
	v_pk_add_f32 v[78:79], v[78:79], v[160:161] op_sel_hi:[1,0] neg_lo:[0,1] neg_hi:[0,1]
	s_nop 1

.Lsel_Nonly_1:
	v_add_u32_e32 v0, s82, v208
	ds_read_b128 v[108:111], v0
	ds_read_b128 v[112:115], v0 offset:4608
	ds_read_b128 v[116:119], v0 offset:32
	ds_read_b128 v[120:123], v0 offset:4640
	s_waitcnt lgkmcnt(3)
	v_mfma_f32_32x32x16_bf16 v[80:95], v[108:111], v[128:131], v[2:17]
	ds_read_b128 v[108:111], v0 offset:64
	s_waitcnt lgkmcnt(3)
	v_mfma_f32_32x32x16_bf16 v[64:79], v[112:115], v[128:131], v[2:17]
	ds_read_b128 v[112:115], v0 offset:4672
	s_waitcnt lgkmcnt(3)
	v_mfma_f32_32x32x16_bf16 v[80:95], v[116:119], v[132:135], v[80:95]
	ds_read_b128 v[116:119], v0 offset:96
	s_waitcnt lgkmcnt(3)
	v_mfma_f32_32x32x16_bf16 v[64:79], v[120:123], v[132:135], v[64:79]
	ds_read_b128 v[120:123], v0 offset:4704
	s_waitcnt lgkmcnt(3)
	v_mfma_f32_32x32x16_bf16 v[80:95], v[108:111], v[136:139], v[80:95]
	s_waitcnt lgkmcnt(2)
	v_mfma_f32_32x32x16_bf16 v[64:79], v[112:115], v[136:139], v[64:79]
	s_waitcnt lgkmcnt(1)
	v_mfma_f32_32x32x16_bf16 v[80:95], v[116:119], v[140:143], v[80:95]
	v_mfma_f32_32x32x16_bf16 v[80:95], v[152:155], v[156:159], v[80:95]
	s_waitcnt lgkmcnt(0)
	v_mfma_f32_32x32x16_bf16 v[64:79], v[120:123], v[140:143], v[64:79]
	v_mfma_f32_32x32x16_bf16 v[64:79], v[152:155], v[156:159], v[64:79]
	s_branch .Lsel_tail_1

.Lsel_nodiag_1c:
	v_add_u32_e32 v187, s81, v208
	ds_read_b128 v[124:127], v187 offset:9216
	ds_read_b128 v[144:147], v187 offset:13824
	ds_read_b128 v[148:151], v187 offset:9248
	v_exp_f32_e32 v238, v238
	v_exp_f32_e32 v239, v239
	v_exp_f32_e32 v240, v240
	v_exp_f32_e32 v241, v241
	v_exp_f32_e32 v242, v242
	v_exp_f32_e32 v243, v243
	v_exp_f32_e32 v244, v244
	v_exp_f32_e32 v245, v245
	v_add_f32_e32 v164, 0, v238
	v_add_f32_e32 v165, 0, v239
	v_add_f32_e32 v164, v240, v164
	v_add_f32_e32 v165, v241, v165
	v_cvt_pk_bf16_f32 v238, v238, v239
	v_cvt_pk_bf16_f32 v239, v240, v241
	v_add_f32_e32 v164, v242, v164
	v_add_f32_e32 v165, v243, v165
	v_add_f32_e32 v164, v244, v164
	v_add_f32_e32 v165, v245, v165
	v_cvt_pk_bf16_f32 v240, v242, v243
	v_cvt_pk_bf16_f32 v241, v244, v245
	v_exp_f32_e32 v246, v246
	v_exp_f32_e32 v247, v247
	s_waitcnt lgkmcnt(2)
	v_mfma_f32_32x32x16_bf16 v[48:63], v[124:127], v[238:241], v[48:63]
	ds_read_b128 v[124:127], v187 offset:13856
	v_exp_f32_e32 v248, v248
	v_exp_f32_e32 v249, v249
	s_waitcnt lgkmcnt(2)
	v_mfma_f32_32x32x16_bf16 v[32:47], v[144:147], v[238:241], v[32:47]
	ds_read_b128 v[144:147], v187 offset:9280
	v_exp_f32_e32 v250, v250
	v_exp_f32_e32 v251, v251
	v_exp_f32_e32 v252, v252
	v_exp_f32_e32 v253, v253
	v_add_f32_e32 v164, v246, v164
	v_add_f32_e32 v165, v247, v165
	v_add_f32_e32 v164, v248, v164
	v_add_f32_e32 v165, v249, v165
	v_cvt_pk_bf16_f32 v246, v246, v247
	v_cvt_pk_bf16_f32 v247, v248, v249
	v_add_f32_e32 v164, v250, v164
	v_add_f32_e32 v165, v251, v165
	v_add_f32_e32 v164, v252, v164
	v_add_f32_e32 v165, v253, v165
	v_cvt_pk_bf16_f32 v248, v250, v251
	v_cvt_pk_bf16_f32 v249, v252, v253
	v_exp_f32_e32 v222, v222
	v_exp_f32_e32 v223, v223
	s_waitcnt lgkmcnt(2)
	v_mfma_f32_32x32x16_bf16 v[48:63], v[148:151], v[246:249], v[48:63]
	ds_read_b128 v[148:151], v187 offset:13888
	v_exp_f32_e32 v224, v224
	v_exp_f32_e32 v225, v225
	s_waitcnt lgkmcnt(2)
	v_mfma_f32_32x32x16_bf16 v[32:47], v[124:127], v[246:249], v[32:47]
	ds_read_b128 v[124:127], v187 offset:9312
	v_exp_f32_e32 v226, v226
	v_exp_f32_e32 v227, v227
	v_exp_f32_e32 v228, v228
	v_exp_f32_e32 v229, v229
	v_add_f32_e32 v164, v222, v164
	v_add_f32_e32 v165, v223, v165
	v_add_f32_e32 v164, v224, v164
	v_add_f32_e32 v165, v225, v165
	v_cvt_pk_bf16_f32 v222, v222, v223
	v_cvt_pk_bf16_f32 v223, v224, v225
	v_add_f32_e32 v164, v226, v164
	v_add_f32_e32 v165, v227, v165
	v_add_f32_e32 v164, v228, v164
	v_add_f32_e32 v165, v229, v165
	v_cvt_pk_bf16_f32 v224, v226, v227
	v_cvt_pk_bf16_f32 v225, v228, v229
	v_exp_f32_e32 v230, v230
	v_exp_f32_e32 v231, v231
	s_waitcnt lgkmcnt(2)
	v_mfma_f32_32x32x16_bf16 v[48:63], v[144:147], v[222:225], v[48:63]
	ds_read_b128 v[144:147], v187 offset:13920
	v_exp_f32_e32 v232, v232
	v_exp_f32_e32 v233, v233
	s_waitcnt lgkmcnt(2)
	v_mfma_f32_32x32x16_bf16 v[32:47], v[148:151], v[222:225], v[32:47]
	v_exp_f32_e32 v234, v234
	v_exp_f32_e32 v235, v235
	v_exp_f32_e32 v236, v236
	v_exp_f32_e32 v237, v237
	v_add_f32_e32 v164, v230, v164
	v_add_f32_e32 v165, v231, v165
	v_add_f32_e32 v164, v232, v164
	v_add_f32_e32 v165, v233, v165
	v_cvt_pk_bf16_f32 v230, v230, v231
	v_cvt_pk_bf16_f32 v231, v232, v233
	v_add_f32_e32 v164, v234, v164
	v_add_f32_e32 v165, v235, v165
	v_add_f32_e32 v164, v236, v164
	v_add_f32_e32 v165, v237, v165
	v_cvt_pk_bf16_f32 v232, v234, v235
	v_cvt_pk_bf16_f32 v233, v236, v237
	s_nop 1
	s_waitcnt lgkmcnt(1)
	v_mfma_f32_32x32x16_bf16 v[48:63], v[124:127], v[230:233], v[48:63]
	s_waitcnt lgkmcnt(0)
	v_mfma_f32_32x32x16_bf16 v[32:47], v[144:147], v[230:233], v[32:47]
	v_add_f32_e32 v164, v164, v165
	v_cndmask_b32_e64 v164, v164, 0, s[72:73]
	v_add_f32_e32 v106, v106, v164
	v_cmp_lt_f32_e32 vcc, 0x43800000, v164
	s_cbranch_vccz .Lsel_noresc_1c
	s_nop 15
	s_nop 15
	v_mov_b32_e32 v107, v164
	s_nop 1
	v_permlane32_swap_b32_e32 v164, v107
	v_add_f32_e32 v164, v164, v107
	v_log_f32_e32 v160, v164
	s_nop 0
	v_max_f32_e32 v160, 0, v160
	v_exp_f32_e64 v162, -v160
	v_sub_f32_e32 v2, v2, v160
	v_sub_f32_e32 v3, v3, v160
	v_sub_f32_e32 v4, v4, v160
	v_sub_f32_e32 v5, v5, v160
	v_sub_f32_e32 v6, v6, v160
	v_sub_f32_e32 v7, v7, v160
	v_sub_f32_e32 v8, v8, v160
	v_sub_f32_e32 v9, v9, v160
	v_sub_f32_e32 v10, v10, v160
	v_sub_f32_e32 v11, v11, v160
	v_sub_f32_e32 v12, v12, v160
	v_sub_f32_e32 v13, v13, v160
	v_sub_f32_e32 v14, v14, v160
	v_sub_f32_e32 v15, v15, v160
	v_sub_f32_e32 v16, v16, v160
	v_sub_f32_e32 v17, v17, v160
	v_mul_f32_e32 v106, v106, v162
	v_pk_mul_f32 v[48:49], v[48:49], v[162:163] op_sel_hi:[1,0]
	v_pk_mul_f32 v[32:33], v[32:33], v[162:163] op_sel_hi:[1,0]
	v_pk_mul_f32 v[50:51], v[50:51], v[162:163] op_sel_hi:[1,0]
	v_pk_mul_f32 v[34:35], v[34:35], v[162:163] op_sel_hi:[1,0]
	v_pk_mul_f32 v[52:53], v[52:53], v[162:163] op_sel_hi:[1,0]
	v_pk_mul_f32 v[36:37], v[36:37], v[162:163] op_sel_hi:[1,0]
	v_pk_mul_f32 v[54:55], v[54:55], v[162:163] op_sel_hi:[1,0]
	v_pk_mul_f32 v[38:39], v[38:39], v[162:163] op_sel_hi:[1,0]
	v_pk_mul_f32 v[56:57], v[56:57], v[162:163] op_sel_hi:[1,0]
	v_pk_mul_f32 v[40:41], v[40:41], v[162:163] op_sel_hi:[1,0]
	v_pk_mul_f32 v[58:59], v[58:59], v[162:163] op_sel_hi:[1,0]
	v_pk_mul_f32 v[42:43], v[42:43], v[162:163] op_sel_hi:[1,0]
	v_pk_mul_f32 v[60:61], v[60:61], v[162:163] op_sel_hi:[1,0]
	v_pk_mul_f32 v[44:45], v[44:45], v[162:163] op_sel_hi:[1,0]
	v_pk_mul_f32 v[62:63], v[62:63], v[162:163] op_sel_hi:[1,0]
	v_pk_mul_f32 v[46:47], v[46:47], v[162:163] op_sel_hi:[1,0]
	s_nop 1
